# M3: same XOR swizzle for the transposed V^T tile (write base + the two B-fragment reads)
# speedup vs baseline: 1.0124x; 1.0028x over previous
.LBB0_733:
	s_or_b64 exec, exec, s[2:3]
	s_waitcnt lgkmcnt(0)
	v_mul_u32_u24_e32 v3, 0x90, v156
	v_lshrrev_b32_e32 v69, 3, v159
	v_bfe_u32 v199, v156, 3, 3
	v_xor_b32_e32 v69, v69, v199
	v_lshlrev_b32_e32 v199, 1, v159
	v_and_b32_e32 v199, 15, v199
	v_lshl_or_b32 v69, v69, 4, v199
	s_waitcnt vmcnt(5)
	v_and_b32_e32 v2, 0xffff, v60
	v_add3_u32 v3, 0, v3, v69
	v_lshrrev_b32_e32 v60, 16, v60
	s_waitcnt vmcnt(4)
	v_lshl_or_b32 v2, v64, 16, v2
	v_and_or_b32 v60, v64, s47, v60
	v_add_u32_e32 v3, 0x8800, v3
	ds_write2_b32 v3, v2, v60 offset1:36
	v_and_b32_e32 v2, 0xffff, v61
	v_lshrrev_b32_e32 v60, 16, v61
	v_lshl_or_b32 v2, v65, 16, v2
	v_and_or_b32 v60, v65, s47, v60
	ds_write2_b32 v3, v2, v60 offset0:72 offset1:108
	v_and_b32_e32 v2, 0xffff, v62
	v_lshrrev_b32_e32 v60, 16, v62
	v_lshl_or_b32 v2, v66, 16, v2
	v_and_or_b32 v60, v66, s47, v60
	ds_write2_b32 v3, v2, v60 offset0:144 offset1:180
	v_and_b32_e32 v2, 0xffff, v63
	v_lshrrev_b32_e32 v60, 16, v63
	s_add_u32 s0, s34, s58
	v_ashrrev_i32_e32 v86, 4, v157
	v_lshl_or_b32 v2, v67, 16, v2
	v_and_or_b32 v60, v67, s47, v60
	s_addc_u32 s1, s35, 0
	v_lshlrev_b32_e32 v82, 1, v156
	v_mov_b32_e32 v83, v0
	v_ashrrev_i32_e32 v87, 31, v86
	ds_write2_b32 v3, v2, v60 offset0:216 offset1:252
	v_lshl_add_u64 v[60:61], s[0:1], 0, v[82:83]
	v_lshl_add_u64 v[84:85], s[26:27], 0, v[86:87]
	v_mad_u64_u32 v[62:63], s[0:1], v84, s33, v[60:61]
	v_mov_b32_e32 v2, v63
	v_mad_u64_u32 v[2:3], s[0:1], v85, s33, v[2:3]
	v_mov_b32_e32 v63, v2
	v_add_u32_e32 v2, 0x200, v157
	v_ashrrev_i32_e32 v2, 4, v2
	v_ashrrev_i32_e32 v3, 31, v2
	v_lshl_add_u64 v[80:81], s[26:27], 0, v[2:3]
	v_mad_u64_u32 v[60:61], s[0:1], v80, s33, v[60:61]
	v_lshlrev_b32_e32 v68, 3, v89
	v_mov_b32_e32 v64, v61
	v_mad_u64_u32 v[64:65], s[0:1], v81, s33, v[64:65]
	v_lshlrev_b32_e32 v3, 1, v68
	v_mul_u32_u24_e32 v68, 0x90, v88
	v_mov_b32_e32 v61, v64
	v_add3_u32 v83, s50, v3, v68
	global_load_dwordx4 v[64:67], v[62:63], off
	s_nop 0
	global_load_dwordx4 v[60:63], v[60:61], off
	s_waitcnt lgkmcnt(0)
	s_barrier
	ds_read_b128 v[68:71], v83
	v_lshl_or_b32 v72, v91, 4, v88
	v_mul_lo_u32 v72, v72, s52
	v_lshrrev_b32_e32 v199, 3, v88
	v_lshl_or_b32 v199, v91, 1, v199
	v_and_b32_e32 v199, 7, v199
	v_lshrrev_b32_e32 v3, 4, v3
	v_xor_b32_e32 v199, v3, v199
	v_lshl_add_u32 v3, v199, 4, v72
	v_xor_b32_e32 v199, 4, v199
	v_lshl_add_u32 v199, v199, 4, v72
	ds_read_b128 v[72:75], v3 offset:34816
	ds_read_b128 v[92:95], v199 offset:34816
	ds_read_b128 v[76:79], v83 offset:64
	ds_read_b128 v[96:99], v83 offset:2304
	ds_read_b128 v[100:103], v83 offset:2368
	ds_read_b128 v[104:107], v83 offset:4608
	ds_read_b128 v[108:111], v83 offset:4672
	ds_read_b128 v[112:115], v83 offset:6912
	ds_read_b128 v[116:119], v83 offset:6976
	s_waitcnt lgkmcnt(8)
	v_mfma_f32_16x16x32_bf16 v[68:71], v[68:71], v[72:75], 0
	v_and_b32_e32 v3, 48, v157
	v_mul_u32_u24_e32 v83, 0x110, v88
	v_add3_u32 v3, 0, v3, v83
	s_waitcnt lgkmcnt(5)
	v_mfma_f32_16x16x32_bf16 v[96:99], v[96:99], v[72:75], 0
	v_lshl_add_u32 v91, v91, 2, s54
	s_waitcnt lgkmcnt(3)
	v_mfma_f32_16x16x32_bf16 v[104:107], v[104:107], v[72:75], 0
	s_waitcnt lgkmcnt(1)
	v_mfma_f32_16x16x32_bf16 v[112:115], v[112:115], v[72:75], 0
	v_mfma_f32_16x16x32_bf16 v[120:123], v[76:79], v[92:95], v[68:71]
	v_mfma_f32_16x16x32_bf16 v[76:79], v[100:103], v[92:95], v[96:99]
	v_mfma_f32_16x16x32_bf16 v[72:75], v[108:111], v[92:95], v[104:107]
	s_waitcnt lgkmcnt(0)
	v_mfma_f32_16x16x32_bf16 v[68:71], v[116:119], v[92:95], v[112:115]
	ds_read_b128 v[92:95], v3
	ds_read_b128 v[96:99], v3 offset:64
	ds_read_b128 v[100:103], v3 offset:4352
	ds_read_b128 v[104:107], v3 offset:4416
	ds_read_b128 v[108:111], v3 offset:8704
	ds_read_b128 v[112:115], v3 offset:8768
	ds_read_b128 v[116:119], v3 offset:13056
	ds_read_b128 v[124:127], v3 offset:13120
	s_waitcnt vmcnt(5) lgkmcnt(7)
	v_mfma_f32_16x16x32_bf16 v[92:95], v[92:95], v[56:59], 0
	s_waitcnt lgkmcnt(5)
	v_mfma_f32_16x16x32_bf16 v[100:103], v[100:103], v[56:59], 0
	s_waitcnt lgkmcnt(3)
	v_mfma_f32_16x16x32_bf16 v[108:111], v[108:111], v[56:59], 0
	s_waitcnt lgkmcnt(1)
	v_mfma_f32_16x16x32_bf16 v[56:59], v[116:119], v[56:59], 0
	s_waitcnt vmcnt(4)
	v_mfma_f32_16x16x32_bf16 v[92:95], v[96:99], v[52:55], v[92:95]
	v_mfma_f32_16x16x32_bf16 v[96:99], v[104:107], v[52:55], v[100:103]
	v_mfma_f32_16x16x32_bf16 v[100:103], v[112:115], v[52:55], v[108:111]
	s_waitcnt lgkmcnt(0)
	v_mfma_f32_16x16x32_bf16 v[52:55], v[124:127], v[52:55], v[56:59]
	s_nop 2
	ds_read_b128 v[56:59], v3 offset:128
	ds_read_b128 v[104:107], v3 offset:192
	s_waitcnt vmcnt(3) lgkmcnt(1)
	v_mfma_f32_16x16x32_bf16 v[56:59], v[56:59], v[48:51], v[92:95]
	s_nop 2
	ds_read_b128 v[92:95], v3 offset:4480
	ds_read_b128 v[108:111], v3 offset:4544
	s_waitcnt lgkmcnt(1)
	v_mfma_f32_16x16x32_bf16 v[92:95], v[92:95], v[48:51], v[96:99]
	s_nop 2
	ds_read_b128 v[96:99], v3 offset:8832
	ds_read_b128 v[112:115], v3 offset:8896
	s_waitcnt lgkmcnt(1)
	v_mfma_f32_16x16x32_bf16 v[96:99], v[96:99], v[48:51], v[100:103]
	s_nop 2
	ds_read_b128 v[100:103], v3 offset:13184
	ds_read_b128 v[116:119], v3 offset:13248
	v_lshl_add_u32 v3, v90, 2, 0
	v_add_u32_e32 v83, 0x17f00, v3
	s_waitcnt vmcnt(2)
	v_mfma_f32_16x16x32_bf16 v[104:107], v[104:107], v[44:47], v[56:59]
	s_nop 2
	v_add_u32_e32 v56, 0x17e00, v3
	v_lshl_add_u32 v57, v89, 6, s53
	s_waitcnt lgkmcnt(1)
	v_mfma_f32_16x16x32_bf16 v[100:103], v[100:103], v[48:51], v[52:55]
	v_add_u32_e32 v3, 0x18000, v3
	v_mfma_f32_16x16x32_bf16 v[52:55], v[108:111], v[44:47], v[92:95]
	v_mfma_f32_16x16x32_bf16 v[48:51], v[112:115], v[44:47], v[96:99]
	s_nop 2
	ds_read_b128 v[94:97], v56
	ds_read_b128 v[56:59], v57
	ds_read_b128 v[108:111], v83
	ds_read_b128 v[112:115], v3
	v_mov_b32_e32 v93, v0
	s_waitcnt lgkmcnt(4)
	v_mfma_f32_16x16x32_bf16 v[44:47], v[116:119], v[44:47], v[100:103]
	s_waitcnt lgkmcnt(3)
	v_mul_f32_e32 v97, 0xbfb8aa3b, v97
	s_waitcnt lgkmcnt(2)
	v_add_f32_e32 v3, v56, v57
	v_mul_f32_e32 v56, 0xbfb8aa3b, v94
	v_exp_f32_e32 v56, v56
	v_add_f32_e32 v57, v58, v59
	v_add_f32_e32 v3, v3, v57
	s_waitcnt lgkmcnt(0)
	v_fmac_f32_e32 v3, v108, v112
	v_max_f32_e64 v3, |v3|, v56
	v_rcp_f32_e32 v3, v3
	v_fma_f32 v56, v104, v108, v120
	v_mov_b32_e32 v57, v0
	v_mul_f32_e32 v59, 0xbfb8aa3b, v95
	v_mul_f32_e32 v56, v56, v3
	v_mul_f32_e32 v3, v56, v56
	v_exp_f32_e32 v59, v59
	v_exp_f32_e32 v97, v97
	v_mov_b32_dpp v57, v3 row_ror:8 row_mask:0xf bank_mask:0xf
	v_or_b32_e32 v3, 1, v90
	v_lshl_add_u32 v58, v3, 4, s53
	ds_read_b128 v[98:101], v58
	v_fmac_f32_e32 v57, v56, v56
	v_fmac_f32_e32 v123, v107, v111
	v_mov_b32_e32 v95, v0
	v_add_f32_dpp v57, v57, v57 row_ror:4 row_mask:0xf bank_mask:0xf bound_ctrl:1
	s_waitcnt lgkmcnt(0)
	v_add_f32_e32 v83, v100, v101
	v_add_f32_dpp v92, v57, v57 row_ror:2 row_mask:0xf bank_mask:0xf bound_ctrl:1
	v_or_b32_e32 v57, 2, v90
	v_lshl_add_u32 v58, v57, 4, s53
	ds_read_b128 v[116:119], v58
	v_add_f32_e32 v58, v98, v99
	v_add_f32_e32 v58, v58, v83
	v_fmac_f32_e32 v58, v109, v113
	v_max_f32_e64 v58, |v58|, v59
	v_rcp_f32_e32 v58, v58
	v_fma_f32 v59, v105, v109, v121
	v_mov_b32_e32 v83, v0
	s_waitcnt lgkmcnt(0)
	v_add_f32_e32 v87, v118, v119
	v_mul_f32_e32 v59, v59, v58
	v_mul_f32_e32 v58, v59, v59
	v_mov_b32_dpp v93, v92 row_ror:1 row_mask:0xf bank_mask:0xf
	s_nop 0
	v_mov_b32_dpp v83, v58 row_ror:8 row_mask:0xf bank_mask:0xf
	v_fmac_f32_e32 v83, v59, v59
	s_nop 1
	v_add_f32_dpp v58, v83, v83 row_ror:4 row_mask:0xf bank_mask:0xf bound_ctrl:1
	v_mul_f32_e32 v83, 0xbfb8aa3b, v96
	v_exp_f32_e32 v83, v83
	v_add_f32_dpp v94, v58, v58 row_ror:2 row_mask:0xf bank_mask:0xf bound_ctrl:1
	v_add_f32_e32 v58, v116, v117
	v_add_f32_e32 v58, v58, v87
	v_fmac_f32_e32 v58, v110, v114
	v_max_f32_e64 v58, |v58|, v83
	v_rcp_f32_e32 v58, v58
	v_or_b32_e32 v87, 3, v90
	v_fma_f32 v83, v106, v110, v122
	v_lshl_add_u32 v98, v87, 4, s53
	v_mul_f32_e32 v58, v83, v58
	ds_read_b128 v[98:101], v98
	v_mul_f32_e32 v83, v58, v58
	v_mov_b32_e32 v96, v0
	v_mov_b32_dpp v95, v94 row_ror:1 row_mask:0xf bank_mask:0xf
	s_nop 0
	v_mov_b32_dpp v96, v83 row_ror:8 row_mask:0xf bank_mask:0xf
	v_fmac_f32_e32 v96, v58, v58
	s_nop 1
	v_add_f32_dpp v83, v96, v96 row_ror:4 row_mask:0xf bank_mask:0xf bound_ctrl:1
	s_nop 1
	v_add_f32_dpp v96, v83, v83 row_ror:2 row_mask:0xf bank_mask:0xf bound_ctrl:1
	s_waitcnt lgkmcnt(0)
	v_add_f32_e32 v83, v98, v99
	v_add_f32_e32 v98, v100, v101
	v_add_f32_e32 v83, v83, v98
	v_fmac_f32_e32 v83, v111, v115
	v_max_f32_e64 v83, |v83|, v97
	v_rcp_f32_e32 v83, v83
	v_mov_b32_e32 v99, v0
	v_mov_b32_e32 v97, v0
	v_mul_f32_e32 v83, v123, v83
	v_mul_f32_e32 v98, v83, v83
	v_mov_b32_dpp v97, v96 row_ror:1 row_mask:0xf bank_mask:0xf
	s_nop 0
	v_mov_b32_dpp v99, v98 row_ror:8 row_mask:0xf bank_mask:0xf
	v_fmac_f32_e32 v99, v83, v83
	s_nop 1
	v_add_f32_dpp v98, v99, v99 row_ror:4 row_mask:0xf bank_mask:0xf bound_ctrl:1
	v_mov_b32_e32 v99, v0
	s_nop 0
	v_add_f32_dpp v98, v98, v98 row_ror:2 row_mask:0xf bank_mask:0xf bound_ctrl:1
	s_nop 1
	v_mov_b32_dpp v99, v98 row_ror:1 row_mask:0xf bank_mask:0xf
	s_and_saveexec_b64 s[0:1], s[12:13]
	s_cbranch_execz .LBB0_735
	v_add_f32_e32 v92, v92, v93
	v_lshl_add_u32 v93, v89, 7, v91
	v_add_f32_e32 v94, v94, v95
	ds_write_b32 v93, v92
	v_lshl_add_u32 v92, v3, 5, v91
	v_add_f32_e32 v96, v96, v97
	ds_write_b32 v92, v94
	v_lshl_add_u32 v92, v57, 5, v91
	v_add_f32_e32 v98, v98, v99
	ds_write_b32 v92, v96
	v_lshl_add_u32 v92, v87, 5, v91
	ds_write_b32 v92, v98
